# weight conversions needed only from P9 on (W_up2, W_dn2, W_br, W_out) moved from P1 into the idle tail of the in-projection GEMM (workgroups without a ninth tile), reusing the P1 item loop
# speedup vs baseline: 1.0060x; 1.0060x over previous
; #define LAS __attribute__((address_space(3)))
; __device__ __forceinline__ unsigned char* karg_ws() { return *(volatile KAS ucptr_t*)((const KAS char*)__builtin_amdgcn_kernarg_segment_ptr() + 264); }
; #define lane opq(lane_now())
; template <int PART>
; __device__ __forceinline__ void prologue(const Params& P, LAS unsigned char* lds, int gw, int NGW, int wave, int lane) {
;     LAS float* scr = (LAS float*)(lds + wave * 16384);
;     unsigned char* ws = karg_ws();
;     constexpr int I_UP = 16 * 176, I_DN = 44 * 32, I_IN = 16 * 257, I_BR = 2 * 16 * 32, I_OUT = 16 * 32, I_ADA = 16 * 288, I_RG = 128;
;     constexpr int NITEMS = 2 * I_UP + 2 * I_DN + I_IN + I_BR + I_OUT + I_ADA + I_RG;
;     constexpr int I_FIRST = 2 * I_UP + 2 * I_DN + I_IN + I_BR + I_OUT;
;     for (int it = gw; it < NITEMS; it += NGW) {
;         int r = it;
;         if (PART == 0) { if (r >= I_ADA) break; r += I_FIRST; } else { if (r >= NITEMS - I_ADA) break; if (r >= I_FIRST) r += I_ADA; }
; __global__ void __launch_bounds__(NTHR, 2) fwd_megakernel(Params P) {
;     ...
;       if (wg >= 36) prologue<1>(P, lds, (wg - 36) * NWAVES + wave, (G - 36) * NWAVES, wave, lane); }
.LBB0_220:
	s_mov_b32 s99, 0
	s_cmp_lt_i32 s2, 36
	s_cbranch_scc1 .LBB0_345
.Lcv_pre:
	v_mov_b32_e32 v3, v166
	s_load_dwordx2 s[14:15], s[0:1], 0x108
	s_add_i32 s26, s72, 0xfffffee0
	s_cmpk_gt_i32 s26, 0x498f
	s_cbranch_scc1 .LBB0_345
	v_and_b32_e32 v0, 31, v3
	v_ashrrev_i32_e32 v2, 5, v3
	v_ashrrev_i32_e32 v1, 3, v3
	v_lshlrev_b32_e32 v3, 3, v3
	v_and_b32_e32 v6, 56, v3
	s_add_i32 s27, s12, 0xfffffee0
	s_lshl_b32 s12, s3, 14
	v_mov_b32_e32 v5, 0
	v_lshlrev_b32_e32 v4, 1, v6
	s_add_i32 s6, s12, 0
	s_movk_i32 s18, 0x84
	v_mul_u32_u24_e32 v3, 0x84, v6
	s_waitcnt lgkmcnt(0)
	v_lshl_add_u64 v[16:17], s[14:15], 0, v[4:5]
	v_lshlrev_b32_e32 v4, 2, v1
	s_mov_b64 s[16:17], 0xc140000
	v_add3_u32 v7, s6, v3, v4
	v_lshl_add_u64 v[10:11], v[16:17], 0, s[16:17]
	s_mov_b64 s[16:17], 0x2600000
	v_mul_lo_u32 v3, v2, s18
	v_lshl_add_u64 v[12:13], v[16:17], 0, s[16:17]
	s_mov_b64 s[16:17], 0x2200000
	v_add_u32_e32 v3, s12, v3
	v_lshlrev_b32_e32 v18, 2, v0
	s_mov_b64 s[4:5], 0x2800000
	v_lshl_add_u64 v[14:15], v[16:17], 0, s[16:17]
	s_mov_b64 s[16:17], 0x1180000
	v_add3_u32 v43, v3, v18, 0
	v_ashrrev_i32_e32 v3, 31, v2
	s_mov_b32 s28, 0x9000
	v_lshl_add_u64 v[8:9], v[16:17], 0, s[4:5]
	v_lshl_add_u64 v[16:17], v[16:17], 0, s[16:17]
	v_mad_i64_i32 v[20:21], s[16:17], v2, s28, 0
	v_lshlrev_b64 v[22:23], 12, v[2:3]
	s_mov_b32 s13, 0
	v_cmp_gt_i32_e64 s[4:5], 32, v1
	v_cmp_gt_i32_e64 s[6:7], 24, v1
	v_add_u32_e32 v40, 8, v1
	v_cmp_gt_i32_e64 s[8:9], 16, v1
	v_add_u32_e32 v41, 16, v1
	v_cmp_gt_i32_e64 s[10:11], 8, v1
	v_add_u32_e32 v42, 24, v1
	v_mov_b32_e32 v19, v5
	v_add_u32_e32 v44, 14, v2
	v_add_u32_e32 v45, 12, v2
	v_add_u32_e32 v46, 10, v2
	v_add_u32_e32 v47, 8, v2
	v_add_u32_e32 v48, 6, v2
	v_add_u32_e32 v49, 4, v2
	v_add_u32_e32 v50, 2, v2
	v_or_b32_e32 v20, v20, v18
	v_or_b32_e32 v22, v22, v18
	s_movk_i32 s29, 0x88
	s_mov_b64 s[16:17], 0x10000
	s_mov_b32 s30, 0x8040
	s_movk_i32 s31, 0xf0
	s_mov_b32 s34, 0xc00000
	s_movk_i32 s35, 0x1600
	s_movk_i32 s36, 0xe8
	s_movk_i32 s37, 0x5800
	s_mov_b32 s38, 0x100000
	s_branch .LBB0_224

; #define INP(k) karg_in(k)
; #define lane opq(lane_now())
; template <int PART>
; __device__ __forceinline__ void prologue(const Params& P, LAS unsigned char* lds, int gw, int NGW, int wave, int lane) {
;     ...
;     for (int it = gw; it < NITEMS; it += NGW) {
;         int r = it;
;         if (PART == 0) { if (r >= I_ADA) break; r += I_FIRST; } else { if (r >= NITEMS - I_ADA) break; if (r >= I_FIRST) r += I_ADA; }
;         if (r < 2 * I_UP) { const int which = r / I_UP; r -= which * I_UP; const int kb = r / 176, nb = r % 176, n0 = nb * 32; const int half = n0 >= FF ? 1 : 0, np = n0 - half * FF;
;             transpose_item(INP(which ? 29 : 11), 2 * FF, kb * 64, n0, 32, (bf16*)(ws + (which ? WS_WUP2 : WS_WUP1)), D, (np >> 7) * 256 + half * 128 + (np & 127), scr, lane, which != 0); continue; }
;         r -= 2 * I_UP;
;         if (r < 2 * I_DN) { const int which = r / I_DN; r -= which * I_DN; const int kb = r / 32, nb = r % 32;
;             transpose_item(INP(which ? 30 : 12), D, kb * 64, nb * 32, 32, (bf16*)(ws + (which ? WS_WDN2 : WS_WDN1)), FF, nb * 32, scr, lane, which != 0); continue; }
;         r -= 2 * I_DN;
;         if (r < I_IN) { const int kb = r / 257, nb = r % 257; int n0, nv, dr;
;             if (nb < 160) { n0 = nb * 32; nv = 32; dr = n0; } else if (nb == 160) { n0 = 5120; nv = 16; dr = 8192; } else { n0 = 5136 + (nb - 161) * 32; nv = 32; dr = 5120 + (nb - 161) * 32; }
;             transpose_item(INP(14), 8208, kb * 64, n0, nv, (bf16*)(ws + WS_WIN), D, dr, scr, lane); continue; }
;         r -= I_IN;
;         if (r < I_BR) { const int which = r / 512; r -= which * 512; const int kb = r / 32, nb = r % 32;
;             transpose_item(INP(26) + (size_t)which * D * D, D, kb * 64, nb * 32, 32, (bf16*)(ws + WS_WBR), D, which * D + nb * 32, scr, lane); continue; }
;         r -= I_BR;
;         if (r < I_OUT) { const int kb = r / 32, nb = r % 32; transpose_item(INP(27), D, kb * 64, nb * 32, 32, (bf16*)(ws + WS_WOUT), D, nb * 32, scr, lane); continue; }
;         r -= I_OUT;
;         if (r < I_ADA) { const int kb = r / 288, nb = r % 288; transpose_item(INP(8), NADA, kb * 64, nb * 32, 32, (bf16*)(ws + WS_WADA), D, nb * 32, scr, lane); continue; }
;         r -= I_ADA;
;         { const int gx = r >> 6, n = (r >> 3) & 7, kb = (r >> 2) & 1, nb = r & 3;
.LBB0_224:
	s_mov_b32 s12, 2
	s_cmp_eq_u32 s99, 0
	s_cbranch_scc0 .Lcv_tailmap
	s_cmpk_gt_i32 s26, 0x210f
	s_cbranch_scc1 .LBB0_319
	s_mov_b32 s22, s26
	s_cmpk_lt_i32 s26, 0xb00
	s_cbranch_scc1 .Lcv_go
	s_add_i32 s22, s26, 0xb00
	s_cmpk_lt_i32 s26, 0x1080
	s_cbranch_scc1 .Lcv_go
	s_add_i32 s22, s26, 0x1080
	s_cmpk_lt_i32 s26, 0x2090
	s_cbranch_scc1 .Lcv_go
	s_add_i32 s22, s26, 0x2880
	s_branch .Lcv_go
.Lcv_tailmap:
	s_cmpk_gt_i32 s26, 0x167f
	s_cbranch_scc1 .LBB0_319
	s_add_i32 s22, s26, 0xb00
	s_cmpk_lt_i32 s26, 0xb00
	s_cbranch_scc1 .Lcv_go
	s_add_i32 s22, s26, 0x1080
	s_cmpk_lt_i32 s26, 0x1080
	s_cbranch_scc1 .Lcv_go
	s_add_i32 s22, s26, 0x2090
.Lcv_go:
	s_cmpk_gt_i32 s22, 0x15ff
	s_mov_b64 s[18:19], -1
	s_cbranch_scc0 .LBB0_310
	s_cmpk_gt_u32 s22, 0x20ff
	s_cbranch_scc0 .LBB0_300
	s_cmpk_gt_u32 s22, 0x310f
	s_cbranch_scc0 .LBB0_269
	s_cmpk_gt_u32 s22, 0x350f
	s_cbranch_scc0 .LBB0_259
	s_cmpk_gt_u32 s22, 0x370f
	s_cbranch_scc0 .LBB0_249
	s_cmpk_gt_u32 s22, 0x490f
	s_cbranch_scc0 .LBB0_239
	s_add_i32 s20, s22, 0xffffb6f0
	s_lshr_b32 s21, s20, 3
	s_cmp_lt_u32 s20, 64
	s_cselect_b32 s12, s29, 0x98
	s_add_u32 s18, s0, s12
	s_addc_u32 s19, s1, 0
	s_load_dwordx2 s[18:19], s[18:19], 0x0
	s_lshl_b32 s12, s22, 4
	s_and_b32 s23, s12, 64
	v_add_u32_e32 v24, s23, v44
	v_add_u32_e32 v26, s23, v45
	v_add_u32_e32 v28, s23, v46
	v_add_u32_e32 v30, s23, v47
	v_add_u32_e32 v32, s23, v48
	v_add_u32_e32 v34, s23, v49
	v_add_u32_e32 v36, s23, v50
	v_add_u32_e32 v52, s23, v2
	s_lshl_b32 s24, s20, 13
	v_ashrrev_i32_e32 v25, 31, v24
	v_ashrrev_i32_e32 v27, 31, v26
	v_ashrrev_i32_e32 v29, 31, v28
	v_ashrrev_i32_e32 v31, 31, v30
	v_ashrrev_i32_e32 v33, 31, v32
	v_ashrrev_i32_e32 v35, 31, v34
	v_ashrrev_i32_e32 v37, 31, v36
	v_ashrrev_i32_e32 v53, 31, v52
	s_and_b32 s12, s24, 0x70000
	s_waitcnt lgkmcnt(0)
	v_lshl_add_u64 v[38:39], s[18:19], 0, v[18:19]
	v_lshlrev_b64 v[24:25], 9, v[24:25]
	s_lshl_b32 s18, s22, 7
	v_lshlrev_b64 v[26:27], 9, v[26:27]
	v_lshlrev_b64 v[28:29], 9, v[28:29]
	v_lshlrev_b64 v[30:31], 9, v[30:31]
	v_lshlrev_b64 v[32:33], 9, v[32:33]
	v_lshlrev_b64 v[34:35], 9, v[34:35]
	v_lshlrev_b64 v[36:37], 9, v[36:37]
	v_lshlrev_b64 v[52:53], 9, v[52:53]
	v_lshl_add_u64 v[24:25], s[12:13], 0, v[24:25]
	s_and_b32 s18, s18, 0x180
	v_lshl_add_u64 v[26:27], s[12:13], 0, v[26:27]
	v_lshl_add_u64 v[28:29], s[12:13], 0, v[28:29]
	v_lshl_add_u64 v[30:31], s[12:13], 0, v[30:31]
	v_lshl_add_u64 v[32:33], s[12:13], 0, v[32:33]
	v_lshl_add_u64 v[34:35], s[12:13], 0, v[34:35]
	v_lshl_add_u64 v[36:37], s[12:13], 0, v[36:37]
	v_lshl_add_u64 v[52:53], s[12:13], 0, v[52:53]
	v_or_b32_e32 v24, s18, v24
	v_or_b32_e32 v26, s18, v26
	v_or_b32_e32 v28, s18, v28
	v_or_b32_e32 v30, s18, v30
	v_or_b32_e32 v32, s18, v32
	v_or_b32_e32 v34, s18, v34
	v_or_b32_e32 v36, s18, v36
	v_or_b32_e32 v52, s18, v52
	v_lshl_add_u64 v[24:25], v[38:39], 0, v[24:25]
	v_lshl_add_u64 v[26:27], v[38:39], 0, v[26:27]
	v_lshl_add_u64 v[28:29], v[38:39], 0, v[28:29]
	v_lshl_add_u64 v[30:31], v[38:39], 0, v[30:31]
	v_lshl_add_u64 v[32:33], v[38:39], 0, v[32:33]
	v_lshl_add_u64 v[34:35], v[38:39], 0, v[34:35]
	v_lshl_add_u64 v[36:37], v[38:39], 0, v[36:37]
	v_lshl_add_u64 v[38:39], v[38:39], 0, v[52:53]
	s_mov_b64 s[18:19], 0
	v_mov_b32_e32 v3, v43

; #define lane opq(lane_now())
; #define GBAR() xcd_barrier(xbar, wave == 0 && lane_now() == 0)
; __device__ __forceinline__ void xcd_barrier(const XcdBarrier& b, bool leader) {
;     asm volatile("s_waitcnt vmcnt(0)" ::: "memory");
;     __syncthreads();
;     if (leader) {
;         unsigned* bar = b.bar;
;         __builtin_amdgcn_s_waitcnt(0);
;         unsigned nloc = b.st[0], nx = b.st[1];
;         if (nloc == 0u) { xcd_barrier_complete(bar, b.x, nloc, nx); b.st[0] = nloc; b.st[1] = nx; }
; __global__ void __launch_bounds__(NTHR, 2) fwd_megakernel(Params P) {
;     ...
;       if (wg >= 36) prologue<1>(P, lds, (wg - 36) * NWAVES + wave, (G - 36) * NWAVES, wave, lane); }
;     }
;     GBAR();
.LBB0_345:
	s_cmp_eq_u32 s99, 1
	s_cbranch_scc1 .Lcv_ret
	s_waitcnt vmcnt(0)
	s_waitcnt vmcnt(0) lgkmcnt(0)
	s_barrier
	s_and_saveexec_b64 s[4:5], s[88:89]
	s_cbranch_execz .LBB0_397
	s_add_i32 s6, 0, 0x23fc0
	v_mov_b32_e32 v0, s6
	s_waitcnt vmcnt(0) expcnt(0) lgkmcnt(0)
	ds_read_b32 v2, v0
	s_add_i32 s6, 0, 0x23fc4
	v_mov_b32_e32 v0, s6
	ds_read_b32 v0, v0
	s_waitcnt lgkmcnt(1)
	v_cmp_ne_u32_e32 vcc, 0, v2
	s_cbranch_vccnz .LBB0_361
	s_add_u32 s6, s76, 0x1000
	s_addc_u32 s7, s77, 0
	s_add_u32 s8, s76, 0x1100
	s_addc_u32 s9, s77, 0
	s_add_u32 s10, s76, 0x1200
	s_addc_u32 s11, s77, 0
	s_mul_i32 s20, s79, s74
	s_add_u32 s12, s76, 0x1300
	s_mul_i32 s20, s20, s78
	s_addc_u32 s13, s77, 0
	s_mov_b32 s21, 1
	v_mov_b32_e32 v16, 0
	s_branch .LBB0_349

; __device__ __forceinline__ float* karg_out() { return *(volatile KAS fptr_t*)((const KAS char*)__builtin_amdgcn_kernarg_segment_ptr() + 256); }
; __global__ void __launch_bounds__(NTHR, 2) fwd_megakernel(Params P) {
;     ...
;     { pg8::Gemm g{H, (const bf16*)(ws + WS_WIN), nullptr, nullptr, D}; pg8::StaticOrder S; S.init(MPAD, NIN, G, wg);
;       EpiIn E{Z, MG, (float*)(ws + WS_ABL), karg_out()}; pg8::gemm_phase(lds, g, S, E, wave); }
;     }
.LBB0_970:
	s_cmpk_lt_u32 s2, 0x61
	s_cbranch_scc1 .Lcv_skip
	s_mov_b32 s99, 1
	s_sub_i32 s72, s2, 0x61
	s_lshl_b32 s72, s72, 3
	s_add_i32 s72, s72, s3
	s_addk_i32 s72, 0x120
	s_movk_i32 s12, 0x618
	s_branch .Lcv_pre
.Lcv_ret:
	s_mov_b32 s99, 0
